# c3sp with static s_setprio 3 instead of 1 for waves 4-7 in GEMM loops
# baseline (speedup 1.0000x reference)
; template <class Epi>
; __device__ __forceinline__ void gemm_phase(PG8_LAS unsigned char* lds, const Gemm g, const StaticOrder& S, const Epi& E) {
;     ...
;         const bool has_next = S.next(ui + 1, nxt);
;         const char* nA = has_next ? (const char*)g.A + (size_t)nxt.pm * tstepA : cA; const char* nB = has_next ? (const char*)g.Bt + (size_t)nxt.pn * tstepB : cB;
;     ...
; #pragma unroll
;         for (int a = 0; a < 2; ++a)
; #pragma unroll
;             for (int b = 0; b < 2; ++b)
; #pragma unroll
;                 for (int m = 0; m < 4; ++m)
; #pragma unroll
;                     for (int n = 0; n < 2; ++n) acc[a][b][m][n] = (f32x4){0.f, 0.f, 0.f, 0.f};
;         cur = nxt; cA = nA; cB = nB; ++ui;
.LBB0_225:
	s_ashr_i32 s53, s52, 31
	v_cmp_lt_i64_e32 vcc, s[6:7], v[152:153]
	s_lshl_b64 s[6:7], s[52:53], 20
	s_add_u32 s56, s76, s6
	s_addc_u32 s57, s77, s7
	s_and_b64 s[6:7], vcc, exec
	s_cselect_b32 s47, s57, s1
	s_cselect_b32 s49, s56, s0
	s_ashr_i32 s51, s50, 31
	s_lshl_b64 s[6:7], s[50:51], 20
	s_add_u32 s58, s80, s6
	s_addc_u32 s59, s81, s7
	s_and_b64 s[6:7], vcc, exec
	s_cselect_b32 s51, s59, s5
	s_cselect_b32 s53, s58, s4
	s_add_u32 s0, s0, 0x80080
	s_addc_u32 s1, s1, 0
	s_add_u32 s60, s4, 0x100
	v_mov_b32_e32 v8, 0
	s_addc_u32 s61, s5, 0
	s_mov_b32 s62, -2
	v_mov_b32_e32 v9, v8
	v_mov_b32_e32 v10, v8
	v_mov_b32_e32 v11, v8
	v_mov_b32_e32 v16, v8
	v_mov_b32_e32 v17, v8
	v_mov_b32_e32 v18, v8
	v_mov_b32_e32 v19, v8
	v_mov_b32_e32 v24, v8
	v_mov_b32_e32 v25, v8
	v_mov_b32_e32 v26, v8
	v_mov_b32_e32 v27, v8
	v_mov_b32_e32 v32, v8
	v_mov_b32_e32 v33, v8
	v_mov_b32_e32 v34, v8
	v_mov_b32_e32 v35, v8
	v_mov_b32_e32 v40, v8
	v_mov_b32_e32 v41, v8
	v_mov_b32_e32 v42, v8
	v_mov_b32_e32 v43, v8
	v_mov_b32_e32 v48, v8
	v_mov_b32_e32 v49, v8
	v_mov_b32_e32 v50, v8
	v_mov_b32_e32 v51, v8
	v_mov_b32_e32 v56, v8
	v_mov_b32_e32 v57, v8
	v_mov_b32_e32 v58, v8
	v_mov_b32_e32 v59, v8
	v_mov_b32_e32 v64, v8
	v_mov_b32_e32 v65, v8
	v_mov_b32_e32 v66, v8
	v_mov_b32_e32 v67, v8
	v_mov_b32_e32 v12, v8
	v_mov_b32_e32 v13, v8
	v_mov_b32_e32 v14, v8
	v_mov_b32_e32 v15, v8
	v_mov_b32_e32 v20, v8
	v_mov_b32_e32 v21, v8
	v_mov_b32_e32 v22, v8
	v_mov_b32_e32 v23, v8
	v_mov_b32_e32 v28, v8
	v_mov_b32_e32 v29, v8
	v_mov_b32_e32 v30, v8
	v_mov_b32_e32 v31, v8
	v_mov_b32_e32 v36, v8
	v_mov_b32_e32 v37, v8
	v_mov_b32_e32 v38, v8
	v_mov_b32_e32 v39, v8
	v_mov_b32_e32 v44, v8
	v_mov_b32_e32 v45, v8
	v_mov_b32_e32 v46, v8
	v_mov_b32_e32 v47, v8
	v_mov_b32_e32 v52, v8
	v_mov_b32_e32 v53, v8
	v_mov_b32_e32 v54, v8
	v_mov_b32_e32 v55, v8
	v_mov_b32_e32 v60, v8
	v_mov_b32_e32 v61, v8
	v_mov_b32_e32 v62, v8
	v_mov_b32_e32 v63, v8
	v_mov_b32_e32 v68, v8
	v_mov_b32_e32 v69, v8
	v_mov_b32_e32 v70, v8
	v_mov_b32_e32 v71, v8
	v_mov_b32_e32 v72, v8
	v_mov_b32_e32 v73, v8
	v_mov_b32_e32 v74, v8
	v_mov_b32_e32 v75, v8
	v_mov_b32_e32 v80, v8
	v_mov_b32_e32 v81, v8
	v_mov_b32_e32 v82, v8
	v_mov_b32_e32 v83, v8
	v_mov_b32_e32 v88, v8
	v_mov_b32_e32 v89, v8
	v_mov_b32_e32 v90, v8
	v_mov_b32_e32 v91, v8
	v_mov_b32_e32 v96, v8
	v_mov_b32_e32 v97, v8
	v_mov_b32_e32 v98, v8
	v_mov_b32_e32 v99, v8
	v_mov_b32_e32 v104, v8
	v_mov_b32_e32 v105, v8
	v_mov_b32_e32 v106, v8
	v_mov_b32_e32 v107, v8
	v_mov_b32_e32 v112, v8
	v_mov_b32_e32 v113, v8
	v_mov_b32_e32 v114, v8
	v_mov_b32_e32 v115, v8
	v_mov_b32_e32 v120, v8
	v_mov_b32_e32 v121, v8
	v_mov_b32_e32 v122, v8
	v_mov_b32_e32 v123, v8
	v_mov_b32_e32 v128, v8
	v_mov_b32_e32 v129, v8
	v_mov_b32_e32 v130, v8
	v_mov_b32_e32 v131, v8
	v_mov_b32_e32 v76, v8
	v_mov_b32_e32 v77, v8
	v_mov_b32_e32 v78, v8
	v_mov_b32_e32 v79, v8
	v_mov_b32_e32 v84, v8
	v_mov_b32_e32 v85, v8
	v_mov_b32_e32 v86, v8
	v_mov_b32_e32 v87, v8
	v_mov_b32_e32 v92, v8
	v_mov_b32_e32 v93, v8
	v_mov_b32_e32 v94, v8
	v_mov_b32_e32 v95, v8
	v_mov_b32_e32 v100, v8
	v_mov_b32_e32 v101, v8
	v_mov_b32_e32 v102, v8
	v_mov_b32_e32 v103, v8
	v_mov_b32_e32 v108, v8
	v_mov_b32_e32 v109, v8
	v_mov_b32_e32 v110, v8
	v_mov_b32_e32 v111, v8
	v_mov_b32_e32 v116, v8
	v_mov_b32_e32 v117, v8
	v_mov_b32_e32 v118, v8
	v_mov_b32_e32 v119, v8
	v_mov_b32_e32 v124, v8
	v_mov_b32_e32 v125, v8
	v_mov_b32_e32 v126, v8
	v_mov_b32_e32 v127, v8
	v_mov_b32_e32 v132, v8
	v_mov_b32_e32 v133, v8
	v_mov_b32_e32 v134, v8
	v_mov_b32_e32 v135, v8
	s_cmp_eq_u32 s101, 1
	s_cbranch_scc0 .Lsp_0
	s_setprio 3

; template <class Epi>
; __device__ __forceinline__ void gemm_phase(PG8_LAS unsigned char* lds, const Gemm g, const StaticOrder& S, const Epi& E) {
;     ...
;         const bool has_next = S.next(ui + 1, nxt);
;         const char* nA = has_next ? (const char*)g.A + (size_t)nxt.pm * tstepA : cA; const char* nB = has_next ? (const char*)g.Bt + (size_t)nxt.pn * tstepB : cB;
;     ...
; #pragma unroll
;         for (int a = 0; a < 2; ++a)
; #pragma unroll
;             for (int b = 0; b < 2; ++b)
; #pragma unroll
;                 for (int m = 0; m < 4; ++m)
; #pragma unroll
;                     for (int n = 0; n < 2; ++n) acc[a][b][m][n] = (f32x4){0.f, 0.f, 0.f, 0.f};
;         cur = nxt; cA = nA; cB = nB; ++ui;
.LBB0_316:
	s_add_u32 s20, s12, 0x160080
	s_addc_u32 s21, s13, 0
	s_add_u32 s48, s10, 0x100
	v_mov_b32_e32 v0, 0
	s_addc_u32 s49, s11, 0
	s_mov_b32 s50, -2
	s_waitcnt lgkmcnt(0)
	v_mov_b32_e32 v1, v0
	v_mov_b32_e32 v2, v0
	v_mov_b32_e32 v3, v0
	v_mov_b32_e32 v4, v0
	v_mov_b32_e32 v5, v0
	v_mov_b32_e32 v6, v0
	v_mov_b32_e32 v7, v0
	v_mov_b32_e32 v16, v0
	v_mov_b32_e32 v17, v0
	v_mov_b32_e32 v18, v0
	v_mov_b32_e32 v19, v0
	v_mov_b32_e32 v20, v0
	v_mov_b32_e32 v21, v0
	v_mov_b32_e32 v22, v0
	v_mov_b32_e32 v23, v0
	v_mov_b32_e32 v32, v0
	v_mov_b32_e32 v33, v0
	v_mov_b32_e32 v34, v0
	v_mov_b32_e32 v35, v0
	v_mov_b32_e32 v36, v0
	v_mov_b32_e32 v37, v0
	v_mov_b32_e32 v38, v0
	v_mov_b32_e32 v39, v0
	v_mov_b32_e32 v48, v0
	v_mov_b32_e32 v49, v0
	v_mov_b32_e32 v50, v0
	v_mov_b32_e32 v51, v0
	v_mov_b32_e32 v52, v0
	v_mov_b32_e32 v53, v0
	v_mov_b32_e32 v54, v0
	v_mov_b32_e32 v55, v0
	v_mov_b32_e32 v12, v0
	v_mov_b32_e32 v13, v0
	v_mov_b32_e32 v14, v0
	v_mov_b32_e32 v15, v0
	v_mov_b32_e32 v8, v0
	v_mov_b32_e32 v9, v0
	v_mov_b32_e32 v10, v0
	v_mov_b32_e32 v11, v0
	v_mov_b32_e32 v28, v0
	v_mov_b32_e32 v29, v0
	v_mov_b32_e32 v30, v0
	v_mov_b32_e32 v31, v0
	v_mov_b32_e32 v24, v0
	v_mov_b32_e32 v25, v0
	v_mov_b32_e32 v26, v0
	v_mov_b32_e32 v27, v0
	v_mov_b32_e32 v44, v0
	v_mov_b32_e32 v45, v0
	v_mov_b32_e32 v46, v0
	v_mov_b32_e32 v47, v0
	v_mov_b32_e32 v40, v0
	v_mov_b32_e32 v41, v0
	v_mov_b32_e32 v42, v0
	v_mov_b32_e32 v43, v0
	v_mov_b32_e32 v56, v0
	v_mov_b32_e32 v57, v0
	v_mov_b32_e32 v58, v0
	v_mov_b32_e32 v59, v0
	v_mov_b32_e32 v60, v0
	v_mov_b32_e32 v61, v0
	v_mov_b32_e32 v62, v0
	v_mov_b32_e32 v63, v0
	v_mov_b32_e32 v64, v0
	v_mov_b32_e32 v65, v0
	v_mov_b32_e32 v66, v0
	v_mov_b32_e32 v67, v0
	v_mov_b32_e32 v68, v0
	v_mov_b32_e32 v69, v0
	v_mov_b32_e32 v70, v0
	v_mov_b32_e32 v71, v0
	v_mov_b32_e32 v80, v0
	v_mov_b32_e32 v81, v0
	v_mov_b32_e32 v82, v0
	v_mov_b32_e32 v83, v0
	v_mov_b32_e32 v84, v0
	v_mov_b32_e32 v85, v0
	v_mov_b32_e32 v86, v0
	v_mov_b32_e32 v87, v0
	v_mov_b32_e32 v96, v0
	v_mov_b32_e32 v97, v0
	v_mov_b32_e32 v98, v0
	v_mov_b32_e32 v99, v0
	v_mov_b32_e32 v100, v0
	v_mov_b32_e32 v101, v0
	v_mov_b32_e32 v102, v0
	v_mov_b32_e32 v103, v0
	v_mov_b32_e32 v112, v0
	v_mov_b32_e32 v113, v0
	v_mov_b32_e32 v114, v0
	v_mov_b32_e32 v115, v0
	v_mov_b32_e32 v116, v0
	v_mov_b32_e32 v117, v0
	v_mov_b32_e32 v118, v0
	v_mov_b32_e32 v119, v0
	v_mov_b32_e32 v76, v0
	v_mov_b32_e32 v77, v0
	v_mov_b32_e32 v78, v0
	v_mov_b32_e32 v79, v0
	v_mov_b32_e32 v72, v0
	v_mov_b32_e32 v73, v0
	v_mov_b32_e32 v74, v0
	v_mov_b32_e32 v75, v0
	v_mov_b32_e32 v92, v0
	v_mov_b32_e32 v93, v0
	v_mov_b32_e32 v94, v0
	v_mov_b32_e32 v95, v0
	v_mov_b32_e32 v88, v0
	v_mov_b32_e32 v89, v0
	v_mov_b32_e32 v90, v0
	v_mov_b32_e32 v91, v0
	v_mov_b32_e32 v108, v0
	v_mov_b32_e32 v109, v0
	v_mov_b32_e32 v110, v0
	v_mov_b32_e32 v111, v0
	v_mov_b32_e32 v104, v0
	v_mov_b32_e32 v105, v0
	v_mov_b32_e32 v106, v0
	v_mov_b32_e32 v107, v0
	v_mov_b32_e32 v120, v0
	v_mov_b32_e32 v121, v0
	v_mov_b32_e32 v122, v0
	v_mov_b32_e32 v123, v0
	v_mov_b32_e32 v124, v0
	v_mov_b32_e32 v125, v0
	v_mov_b32_e32 v126, v0
	v_mov_b32_e32 v127, v0
	s_cmp_eq_u32 s101, 1
	s_cbranch_scc0 .Lsp_1
	s_setprio 3

; template <class Epi>
; __device__ __forceinline__ void gemm_phase(PG8_LAS unsigned char* lds, const Gemm g, const StaticOrder& S, const Epi& E) {
;     ...
;         const bool has_next = S.next(ui + 1, nxt);
;         const char* nA = has_next ? (const char*)g.A + (size_t)nxt.pm * tstepA : cA; const char* nB = has_next ? (const char*)g.Bt + (size_t)nxt.pn * tstepB : cB;
;     ...
; #pragma unroll
;         for (int a = 0; a < 2; ++a)
; #pragma unroll
;             for (int b = 0; b < 2; ++b)
; #pragma unroll
;                 for (int m = 0; m < 4; ++m)
; #pragma unroll
;                     for (int n = 0; n < 2; ++n) acc[a][b][m][n] = (f32x4){0.f, 0.f, 0.f, 0.f};
;         cur = nxt; cA = nA; cB = nB; ++ui;
.LBB0_412:
	s_ashr_i32 s57, s56, 31
	v_cmp_lt_i64_e32 vcc, s[6:7], v[144:145]
	s_lshl_b64 s[6:7], s[56:57], 20
	s_add_u32 s58, s76, s6
	s_addc_u32 s59, s77, s7
	s_and_b64 s[6:7], vcc, exec
	s_cselect_b32 s53, s59, s1
	s_cselect_b32 s57, s58, s0
	s_ashr_i32 s55, s54, 31
	s_lshl_b64 s[6:7], s[54:55], 20
	v_readlane_b32 s48, v253, 34
	v_readlane_b32 s49, v253, 35
	s_add_u32 s60, s48, s6
	s_addc_u32 s61, s49, s7
	s_and_b64 s[6:7], vcc, exec
	s_cselect_b32 s55, s61, s5
	s_cselect_b32 s63, s60, s4
	s_add_u32 s0, s0, 0x80080
	s_addc_u32 s1, s1, 0
	s_add_u32 s65, s4, 0x100
	v_mov_b32_e32 v0, 0
	s_addc_u32 s66, s5, 0
	s_mov_b32 s67, -2
	v_mov_b32_e32 v1, v0
	v_mov_b32_e32 v2, v0
	v_mov_b32_e32 v3, v0
	v_mov_b32_e32 v4, v0
	v_mov_b32_e32 v5, v0
	v_mov_b32_e32 v6, v0
	v_mov_b32_e32 v7, v0
	v_mov_b32_e32 v16, v0
	v_mov_b32_e32 v17, v0
	v_mov_b32_e32 v18, v0
	v_mov_b32_e32 v19, v0
	v_mov_b32_e32 v20, v0
	v_mov_b32_e32 v21, v0
	v_mov_b32_e32 v22, v0
	v_mov_b32_e32 v23, v0
	v_mov_b32_e32 v32, v0
	v_mov_b32_e32 v33, v0
	v_mov_b32_e32 v34, v0
	v_mov_b32_e32 v35, v0
	v_mov_b32_e32 v36, v0
	v_mov_b32_e32 v37, v0
	v_mov_b32_e32 v38, v0
	v_mov_b32_e32 v39, v0
	v_mov_b32_e32 v48, v0
	v_mov_b32_e32 v49, v0
	v_mov_b32_e32 v50, v0
	v_mov_b32_e32 v51, v0
	v_mov_b32_e32 v52, v0
	v_mov_b32_e32 v53, v0
	v_mov_b32_e32 v54, v0
	v_mov_b32_e32 v55, v0
	v_mov_b32_e32 v8, v0
	v_mov_b32_e32 v9, v0
	v_mov_b32_e32 v10, v0
	v_mov_b32_e32 v11, v0
	v_mov_b32_e32 v12, v0
	v_mov_b32_e32 v13, v0
	v_mov_b32_e32 v14, v0
	v_mov_b32_e32 v15, v0
	v_mov_b32_e32 v24, v0
	v_mov_b32_e32 v25, v0
	v_mov_b32_e32 v26, v0
	v_mov_b32_e32 v27, v0
	v_mov_b32_e32 v28, v0
	v_mov_b32_e32 v29, v0
	v_mov_b32_e32 v30, v0
	v_mov_b32_e32 v31, v0
	v_mov_b32_e32 v40, v0
	v_mov_b32_e32 v41, v0
	v_mov_b32_e32 v42, v0
	v_mov_b32_e32 v43, v0
	v_mov_b32_e32 v44, v0
	v_mov_b32_e32 v45, v0
	v_mov_b32_e32 v46, v0
	v_mov_b32_e32 v47, v0
	v_mov_b32_e32 v56, v0
	v_mov_b32_e32 v57, v0
	v_mov_b32_e32 v58, v0
	v_mov_b32_e32 v59, v0
	v_mov_b32_e32 v60, v0
	v_mov_b32_e32 v61, v0
	v_mov_b32_e32 v62, v0
	v_mov_b32_e32 v63, v0
	v_mov_b32_e32 v64, v0
	v_mov_b32_e32 v65, v0
	v_mov_b32_e32 v66, v0
	v_mov_b32_e32 v67, v0
	v_mov_b32_e32 v68, v0
	v_mov_b32_e32 v69, v0
	v_mov_b32_e32 v70, v0
	v_mov_b32_e32 v71, v0
	v_mov_b32_e32 v80, v0
	v_mov_b32_e32 v81, v0
	v_mov_b32_e32 v82, v0
	v_mov_b32_e32 v83, v0
	v_mov_b32_e32 v84, v0
	v_mov_b32_e32 v85, v0
	v_mov_b32_e32 v86, v0
	v_mov_b32_e32 v87, v0
	v_mov_b32_e32 v96, v0
	v_mov_b32_e32 v97, v0
	v_mov_b32_e32 v98, v0
	v_mov_b32_e32 v99, v0
	v_mov_b32_e32 v100, v0
	v_mov_b32_e32 v101, v0
	v_mov_b32_e32 v102, v0
	v_mov_b32_e32 v103, v0
	v_mov_b32_e32 v112, v0
	v_mov_b32_e32 v113, v0
	v_mov_b32_e32 v114, v0
	v_mov_b32_e32 v115, v0
	v_mov_b32_e32 v116, v0
	v_mov_b32_e32 v117, v0
	v_mov_b32_e32 v118, v0
	v_mov_b32_e32 v119, v0
	v_mov_b32_e32 v72, v0
	v_mov_b32_e32 v73, v0
	v_mov_b32_e32 v74, v0
	v_mov_b32_e32 v75, v0
	v_mov_b32_e32 v76, v0
	v_mov_b32_e32 v77, v0
	v_mov_b32_e32 v78, v0
	v_mov_b32_e32 v79, v0
	v_mov_b32_e32 v88, v0
	v_mov_b32_e32 v89, v0
	v_mov_b32_e32 v90, v0
	v_mov_b32_e32 v91, v0
	v_mov_b32_e32 v92, v0
	v_mov_b32_e32 v93, v0
	v_mov_b32_e32 v94, v0
	v_mov_b32_e32 v95, v0
	v_mov_b32_e32 v104, v0
	v_mov_b32_e32 v105, v0
	v_mov_b32_e32 v106, v0
	v_mov_b32_e32 v107, v0
	v_mov_b32_e32 v108, v0
	v_mov_b32_e32 v109, v0
	v_mov_b32_e32 v110, v0
	v_mov_b32_e32 v111, v0
	v_mov_b32_e32 v120, v0
	v_mov_b32_e32 v121, v0
	v_mov_b32_e32 v122, v0
	v_mov_b32_e32 v123, v0
	v_mov_b32_e32 v124, v0
	v_mov_b32_e32 v125, v0
	v_mov_b32_e32 v126, v0
	v_mov_b32_e32 v127, v0
	s_cmp_eq_u32 s101, 1
	s_cbranch_scc0 .Lsp_2
	s_setprio 3

; template <class Epi>
; __device__ __forceinline__ void gemm_phase(PG8_LAS unsigned char* lds, const Gemm g, const StaticOrder& S, const Epi& E) {
;     ...
;         const bool has_next = S.next(ui + 1, nxt);
;         const char* nA = has_next ? (const char*)g.A + (size_t)nxt.pm * tstepA : cA; const char* nB = has_next ? (const char*)g.Bt + (size_t)nxt.pn * tstepB : cB;
;     ...
; #pragma unroll
;         for (int a = 0; a < 2; ++a)
; #pragma unroll
;             for (int b = 0; b < 2; ++b)
; #pragma unroll
;                 for (int m = 0; m < 4; ++m)
; #pragma unroll
;                     for (int n = 0; n < 2; ++n) acc[a][b][m][n] = (f32x4){0.f, 0.f, 0.f, 0.f};
;         cur = nxt; cA = nA; cB = nB; ++ui;
.LBB0_903:
	s_ashr_i32 s15, s14, 31
	v_cmp_lt_i64_e32 vcc, s[16:17], v[160:161]
	s_lshl_b64 s[16:17], s[14:15], 19
	s_add_u32 s16, s80, s16
	s_addc_u32 s17, s81, s17
	s_and_b64 s[18:19], vcc, exec
	s_cselect_b32 s15, s17, s29
	s_cselect_b32 s54, s16, s28
	s_ashr_i32 s13, s12, 31
	s_lshl_b64 s[18:19], s[12:13], 19
	s_add_u32 s18, s64, s18
	s_addc_u32 s19, s65, s19
	s_and_b64 s[30:31], vcc, exec
	s_cselect_b32 s13, s19, s23
	s_cselect_b32 s55, s18, s22
	s_add_u32 s28, s28, 0x40080
	s_addc_u32 s29, s29, 0
	s_add_u32 s56, s22, 0x100
	v_mov_b32_e32 v0, 0
	s_addc_u32 s57, s23, 0
	s_mov_b32 s58, -2
	v_mov_b32_e32 v1, v0
	v_mov_b32_e32 v2, v0
	v_mov_b32_e32 v3, v0
	v_mov_b32_e32 v4, v0
	v_mov_b32_e32 v5, v0
	v_mov_b32_e32 v6, v0
	v_mov_b32_e32 v7, v0
	v_mov_b32_e32 v16, v0
	v_mov_b32_e32 v17, v0
	v_mov_b32_e32 v18, v0
	v_mov_b32_e32 v19, v0
	v_mov_b32_e32 v20, v0
	v_mov_b32_e32 v21, v0
	v_mov_b32_e32 v22, v0
	v_mov_b32_e32 v23, v0
	v_mov_b32_e32 v32, v0
	v_mov_b32_e32 v33, v0
	v_mov_b32_e32 v34, v0
	v_mov_b32_e32 v35, v0
	v_mov_b32_e32 v36, v0
	v_mov_b32_e32 v37, v0
	v_mov_b32_e32 v38, v0
	v_mov_b32_e32 v39, v0
	v_mov_b32_e32 v48, v0
	v_mov_b32_e32 v49, v0
	v_mov_b32_e32 v50, v0
	v_mov_b32_e32 v51, v0
	v_mov_b32_e32 v52, v0
	v_mov_b32_e32 v53, v0
	v_mov_b32_e32 v54, v0
	v_mov_b32_e32 v55, v0
	v_mov_b32_e32 v8, v0
	v_mov_b32_e32 v9, v0
	v_mov_b32_e32 v10, v0
	v_mov_b32_e32 v11, v0
	v_mov_b32_e32 v12, v0
	v_mov_b32_e32 v13, v0
	v_mov_b32_e32 v14, v0
	v_mov_b32_e32 v15, v0
	v_mov_b32_e32 v24, v0
	v_mov_b32_e32 v25, v0
	v_mov_b32_e32 v26, v0
	v_mov_b32_e32 v27, v0
	v_mov_b32_e32 v28, v0
	v_mov_b32_e32 v29, v0
	v_mov_b32_e32 v30, v0
	v_mov_b32_e32 v31, v0
	v_mov_b32_e32 v40, v0
	v_mov_b32_e32 v41, v0
	v_mov_b32_e32 v42, v0
	v_mov_b32_e32 v43, v0
	v_mov_b32_e32 v44, v0
	v_mov_b32_e32 v45, v0
	v_mov_b32_e32 v46, v0
	v_mov_b32_e32 v47, v0
	v_mov_b32_e32 v56, v0
	v_mov_b32_e32 v57, v0
	v_mov_b32_e32 v58, v0
	v_mov_b32_e32 v59, v0
	v_mov_b32_e32 v60, v0
	v_mov_b32_e32 v61, v0
	v_mov_b32_e32 v62, v0
	v_mov_b32_e32 v63, v0
	v_mov_b32_e32 v64, v0
	v_mov_b32_e32 v65, v0
	v_mov_b32_e32 v66, v0
	v_mov_b32_e32 v67, v0
	v_mov_b32_e32 v68, v0
	v_mov_b32_e32 v69, v0
	v_mov_b32_e32 v70, v0
	v_mov_b32_e32 v71, v0
	v_mov_b32_e32 v80, v0
	v_mov_b32_e32 v81, v0
	v_mov_b32_e32 v82, v0
	v_mov_b32_e32 v83, v0
	v_mov_b32_e32 v84, v0
	v_mov_b32_e32 v85, v0
	v_mov_b32_e32 v86, v0
	v_mov_b32_e32 v87, v0
	v_mov_b32_e32 v96, v0
	v_mov_b32_e32 v97, v0
	v_mov_b32_e32 v98, v0
	v_mov_b32_e32 v99, v0
	v_mov_b32_e32 v100, v0
	v_mov_b32_e32 v101, v0
	v_mov_b32_e32 v102, v0
	v_mov_b32_e32 v103, v0
	v_mov_b32_e32 v112, v0
	v_mov_b32_e32 v113, v0
	v_mov_b32_e32 v114, v0
	v_mov_b32_e32 v115, v0
	v_mov_b32_e32 v116, v0
	v_mov_b32_e32 v117, v0
	v_mov_b32_e32 v118, v0
	v_mov_b32_e32 v119, v0
	v_mov_b32_e32 v72, v0
	v_mov_b32_e32 v73, v0
	v_mov_b32_e32 v74, v0
	v_mov_b32_e32 v75, v0
	v_mov_b32_e32 v76, v0
	v_mov_b32_e32 v77, v0
	v_mov_b32_e32 v78, v0
	v_mov_b32_e32 v79, v0
	v_mov_b32_e32 v88, v0
	v_mov_b32_e32 v89, v0
	v_mov_b32_e32 v90, v0
	v_mov_b32_e32 v91, v0
	v_mov_b32_e32 v92, v0
	v_mov_b32_e32 v93, v0
	v_mov_b32_e32 v94, v0
	v_mov_b32_e32 v95, v0
	v_mov_b32_e32 v104, v0
	v_mov_b32_e32 v105, v0
	v_mov_b32_e32 v106, v0
	v_mov_b32_e32 v107, v0
	v_mov_b32_e32 v108, v0
	v_mov_b32_e32 v109, v0
	v_mov_b32_e32 v110, v0
	v_mov_b32_e32 v111, v0
	v_mov_b32_e32 v120, v0
	v_mov_b32_e32 v121, v0
	v_mov_b32_e32 v122, v0
	v_mov_b32_e32 v123, v0
	v_mov_b32_e32 v124, v0
	v_mov_b32_e32 v125, v0
	v_mov_b32_e32 v126, v0
	v_mov_b32_e32 v127, v0
	s_cmp_eq_u32 s101, 1
	s_cbranch_scc0 .Lsp_3
	s_setprio 3

; template <class Epi>
; __device__ __forceinline__ void gemm_phase(PG8_LAS unsigned char* lds, const Gemm g, const StaticOrder& S, const Epi& E) {
;     ...
;         const bool has_next = S.next(ui + 1, nxt);
;         const char* nA = has_next ? (const char*)g.A + (size_t)nxt.pm * tstepA : cA; const char* nB = has_next ? (const char*)g.Bt + (size_t)nxt.pn * tstepB : cB;
;     ...
; #pragma unroll
;         for (int a = 0; a < 2; ++a)
; #pragma unroll
;             for (int b = 0; b < 2; ++b)
; #pragma unroll
;                 for (int m = 0; m < 4; ++m)
; #pragma unroll
;                     for (int n = 0; n < 2; ++n) acc[a][b][m][n] = (f32x4){0.f, 0.f, 0.f, 0.f};
;         cur = nxt; cA = nA; cB = nB; ++ui;
.LBB0_924:
	s_ashr_i32 s17, s16, 31
	v_cmp_lt_i64_e32 vcc, s[18:19], v[182:183]
	s_lshl_b64 s[18:19], s[16:17], 19
	s_add_u32 s18, s90, s18
	s_addc_u32 s19, s91, s19
	s_and_b64 s[20:21], vcc, exec
	s_cselect_b32 s17, s19, s31
	s_cselect_b32 s57, s18, s30
	s_ashr_i32 s15, s14, 31
	s_lshl_b64 s[20:21], s[14:15], 19
	v_readlane_b32 s34, v253, 38
	v_readlane_b32 s35, v253, 39
	s_add_u32 s20, s34, s20
	s_addc_u32 s21, s35, s21
	s_and_b64 s[34:35], vcc, exec
	s_cselect_b32 s15, s21, s23
	s_cselect_b32 s58, s20, s22
	s_add_u32 s30, s30, 0x40080
	s_addc_u32 s31, s31, 0
	s_add_u32 s59, s22, 0x100
	v_mov_b32_e32 v0, 0
	s_addc_u32 s60, s23, 0
	s_mov_b32 s61, -2
	v_mov_b32_e32 v1, v0
	v_mov_b32_e32 v2, v0
	v_mov_b32_e32 v3, v0
	v_mov_b32_e32 v4, v0
	v_mov_b32_e32 v5, v0
	v_mov_b32_e32 v6, v0
	v_mov_b32_e32 v7, v0
	v_mov_b32_e32 v16, v0
	v_mov_b32_e32 v17, v0
	v_mov_b32_e32 v18, v0
	v_mov_b32_e32 v19, v0
	v_mov_b32_e32 v20, v0
	v_mov_b32_e32 v21, v0
	v_mov_b32_e32 v22, v0
	v_mov_b32_e32 v23, v0
	v_mov_b32_e32 v32, v0
	v_mov_b32_e32 v33, v0
	v_mov_b32_e32 v34, v0
	v_mov_b32_e32 v35, v0
	v_mov_b32_e32 v36, v0
	v_mov_b32_e32 v37, v0
	v_mov_b32_e32 v38, v0
	v_mov_b32_e32 v39, v0
	v_mov_b32_e32 v48, v0
	v_mov_b32_e32 v49, v0
	v_mov_b32_e32 v50, v0
	v_mov_b32_e32 v51, v0
	v_mov_b32_e32 v52, v0
	v_mov_b32_e32 v53, v0
	v_mov_b32_e32 v54, v0
	v_mov_b32_e32 v55, v0
	v_mov_b32_e32 v8, v0
	v_mov_b32_e32 v9, v0
	v_mov_b32_e32 v10, v0
	v_mov_b32_e32 v11, v0
	v_mov_b32_e32 v12, v0
	v_mov_b32_e32 v13, v0
	v_mov_b32_e32 v14, v0
	v_mov_b32_e32 v15, v0
	v_mov_b32_e32 v24, v0
	v_mov_b32_e32 v25, v0
	v_mov_b32_e32 v26, v0
	v_mov_b32_e32 v27, v0
	v_mov_b32_e32 v28, v0
	v_mov_b32_e32 v29, v0
	v_mov_b32_e32 v30, v0
	v_mov_b32_e32 v31, v0
	v_mov_b32_e32 v40, v0
	v_mov_b32_e32 v41, v0
	v_mov_b32_e32 v42, v0
	v_mov_b32_e32 v43, v0
	v_mov_b32_e32 v44, v0
	v_mov_b32_e32 v45, v0
	v_mov_b32_e32 v46, v0
	v_mov_b32_e32 v47, v0
	v_mov_b32_e32 v56, v0
	v_mov_b32_e32 v57, v0
	v_mov_b32_e32 v58, v0
	v_mov_b32_e32 v59, v0
	v_mov_b32_e32 v60, v0
	v_mov_b32_e32 v61, v0
	v_mov_b32_e32 v62, v0
	v_mov_b32_e32 v63, v0
	v_mov_b32_e32 v64, v0
	v_mov_b32_e32 v65, v0
	v_mov_b32_e32 v66, v0
	v_mov_b32_e32 v67, v0
	v_mov_b32_e32 v68, v0
	v_mov_b32_e32 v69, v0
	v_mov_b32_e32 v70, v0
	v_mov_b32_e32 v71, v0
	v_mov_b32_e32 v80, v0
	v_mov_b32_e32 v81, v0
	v_mov_b32_e32 v82, v0
	v_mov_b32_e32 v83, v0
	v_mov_b32_e32 v84, v0
	v_mov_b32_e32 v85, v0
	v_mov_b32_e32 v86, v0
	v_mov_b32_e32 v87, v0
	v_mov_b32_e32 v96, v0
	v_mov_b32_e32 v97, v0
	v_mov_b32_e32 v98, v0
	v_mov_b32_e32 v99, v0
	v_mov_b32_e32 v100, v0
	v_mov_b32_e32 v101, v0
	v_mov_b32_e32 v102, v0
	v_mov_b32_e32 v103, v0
	v_mov_b32_e32 v112, v0
	v_mov_b32_e32 v113, v0
	v_mov_b32_e32 v114, v0
	v_mov_b32_e32 v115, v0
	v_mov_b32_e32 v116, v0
	v_mov_b32_e32 v117, v0
	v_mov_b32_e32 v118, v0
	v_mov_b32_e32 v119, v0
	v_mov_b32_e32 v72, v0
	v_mov_b32_e32 v73, v0
	v_mov_b32_e32 v74, v0
	v_mov_b32_e32 v75, v0
	v_mov_b32_e32 v76, v0
	v_mov_b32_e32 v77, v0
	v_mov_b32_e32 v78, v0
	v_mov_b32_e32 v79, v0
	v_mov_b32_e32 v88, v0
	v_mov_b32_e32 v89, v0
	v_mov_b32_e32 v90, v0
	v_mov_b32_e32 v91, v0
	v_mov_b32_e32 v92, v0
	v_mov_b32_e32 v93, v0
	v_mov_b32_e32 v94, v0
	v_mov_b32_e32 v95, v0
	v_mov_b32_e32 v104, v0
	v_mov_b32_e32 v105, v0
	v_mov_b32_e32 v106, v0
	v_mov_b32_e32 v107, v0
	v_mov_b32_e32 v108, v0
	v_mov_b32_e32 v109, v0
	v_mov_b32_e32 v110, v0
	v_mov_b32_e32 v111, v0
	v_mov_b32_e32 v120, v0
	v_mov_b32_e32 v121, v0
	v_mov_b32_e32 v122, v0
	v_mov_b32_e32 v123, v0
	v_mov_b32_e32 v124, v0
	v_mov_b32_e32 v125, v0
	v_mov_b32_e32 v126, v0
	v_mov_b32_e32 v127, v0
	s_waitcnt vmcnt(0)
	s_cmp_eq_u32 s101, 1
	s_cbranch_scc0 .Lsp_4
	s_setprio 3

; template <class Epi>
; __device__ __forceinline__ void gemm_phase(PG8_LAS unsigned char* lds, const Gemm g, const StaticOrder& S, const Epi& E) {
;     ...
;         const bool has_next = S.next(ui + 1, nxt);
;         const char* nA = has_next ? (const char*)g.A + (size_t)nxt.pm * tstepA : cA; const char* nB = has_next ? (const char*)g.Bt + (size_t)nxt.pn * tstepB : cB;
;     ...
; #pragma unroll
;         for (int a = 0; a < 2; ++a)
; #pragma unroll
;             for (int b = 0; b < 2; ++b)
; #pragma unroll
;                 for (int m = 0; m < 4; ++m)
; #pragma unroll
;                     for (int n = 0; n < 2; ++n) acc[a][b][m][n] = (f32x4){0.f, 0.f, 0.f, 0.f};
;         cur = nxt; cA = nA; cB = nB; ++ui;
.LBB0_1002:
	s_ashr_i32 s15, s14, 31
	v_cmp_lt_i64_e32 vcc, s[16:17], v[164:165]
	s_lshl_b64 s[16:17], s[14:15], 21
	s_add_u32 s16, s46, s16
	s_addc_u32 s17, s47, s17
	s_and_b64 s[18:19], vcc, exec
	s_cselect_b32 s15, s17, s29
	s_cselect_b32 s21, s16, s28
	s_ashr_i32 s13, s12, 31
	s_lshl_b64 s[18:19], s[12:13], 20
	v_readlane_b32 s30, v253, 40
	v_readlane_b32 s31, v253, 41
	s_add_u32 s18, s30, s18
	s_addc_u32 s19, s31, s19
	s_and_b64 s[30:31], vcc, exec
	s_cselect_b32 s13, s19, s23
	s_cselect_b32 s53, s18, s22
	s_add_u32 s28, s28, 0x100080
	s_addc_u32 s29, s29, 0
	s_add_u32 s54, s22, 0x100
	v_mov_b32_e32 v0, 0
	s_addc_u32 s55, s23, 0
	s_mov_b32 s56, -2
	s_waitcnt lgkmcnt(0)
	v_mov_b32_e32 v1, v0
	v_mov_b32_e32 v2, v0
	v_mov_b32_e32 v3, v0
	v_mov_b32_e32 v4, v0
	v_mov_b32_e32 v5, v0
	v_mov_b32_e32 v6, v0
	v_mov_b32_e32 v7, v0
	v_mov_b32_e32 v16, v0
	v_mov_b32_e32 v17, v0
	v_mov_b32_e32 v18, v0
	v_mov_b32_e32 v19, v0
	v_mov_b32_e32 v20, v0
	v_mov_b32_e32 v21, v0
	v_mov_b32_e32 v22, v0
	v_mov_b32_e32 v23, v0
	v_mov_b32_e32 v32, v0
	v_mov_b32_e32 v33, v0
	v_mov_b32_e32 v34, v0
	v_mov_b32_e32 v35, v0
	v_mov_b32_e32 v36, v0
	v_mov_b32_e32 v37, v0
	v_mov_b32_e32 v38, v0
	v_mov_b32_e32 v39, v0
	v_mov_b32_e32 v48, v0
	v_mov_b32_e32 v49, v0
	v_mov_b32_e32 v50, v0
	v_mov_b32_e32 v51, v0
	v_mov_b32_e32 v52, v0
	v_mov_b32_e32 v53, v0
	v_mov_b32_e32 v54, v0
	v_mov_b32_e32 v55, v0
	v_mov_b32_e32 v12, v0
	v_mov_b32_e32 v13, v0
	v_mov_b32_e32 v14, v0
	v_mov_b32_e32 v15, v0
	v_mov_b32_e32 v8, v0
	v_mov_b32_e32 v9, v0
	v_mov_b32_e32 v10, v0
	v_mov_b32_e32 v11, v0
	v_mov_b32_e32 v28, v0
	v_mov_b32_e32 v29, v0
	v_mov_b32_e32 v30, v0
	v_mov_b32_e32 v31, v0
	v_mov_b32_e32 v24, v0
	v_mov_b32_e32 v25, v0
	v_mov_b32_e32 v26, v0
	v_mov_b32_e32 v27, v0
	v_mov_b32_e32 v44, v0
	v_mov_b32_e32 v45, v0
	v_mov_b32_e32 v46, v0
	v_mov_b32_e32 v47, v0
	v_mov_b32_e32 v40, v0
	v_mov_b32_e32 v41, v0
	v_mov_b32_e32 v42, v0
	v_mov_b32_e32 v43, v0
	v_mov_b32_e32 v56, v0
	v_mov_b32_e32 v57, v0
	v_mov_b32_e32 v58, v0
	v_mov_b32_e32 v59, v0
	v_mov_b32_e32 v60, v0
	v_mov_b32_e32 v61, v0
	v_mov_b32_e32 v62, v0
	v_mov_b32_e32 v63, v0
	v_mov_b32_e32 v64, v0
	v_mov_b32_e32 v65, v0
	v_mov_b32_e32 v66, v0
	v_mov_b32_e32 v67, v0
	v_mov_b32_e32 v68, v0
	v_mov_b32_e32 v69, v0
	v_mov_b32_e32 v70, v0
	v_mov_b32_e32 v71, v0
	v_mov_b32_e32 v80, v0
	v_mov_b32_e32 v81, v0
	v_mov_b32_e32 v82, v0
	v_mov_b32_e32 v83, v0
	v_mov_b32_e32 v84, v0
	v_mov_b32_e32 v85, v0
	v_mov_b32_e32 v86, v0
	v_mov_b32_e32 v87, v0
	v_mov_b32_e32 v96, v0
	v_mov_b32_e32 v97, v0
	v_mov_b32_e32 v98, v0
	v_mov_b32_e32 v99, v0
	v_mov_b32_e32 v100, v0
	v_mov_b32_e32 v101, v0
	v_mov_b32_e32 v102, v0
	v_mov_b32_e32 v103, v0
	v_mov_b32_e32 v112, v0
	v_mov_b32_e32 v113, v0
	v_mov_b32_e32 v114, v0
	v_mov_b32_e32 v115, v0
	v_mov_b32_e32 v116, v0
	v_mov_b32_e32 v117, v0
	v_mov_b32_e32 v118, v0
	v_mov_b32_e32 v119, v0
	v_mov_b32_e32 v76, v0
	v_mov_b32_e32 v77, v0
	v_mov_b32_e32 v78, v0
	v_mov_b32_e32 v79, v0
	v_mov_b32_e32 v72, v0
	v_mov_b32_e32 v73, v0
	v_mov_b32_e32 v74, v0
	v_mov_b32_e32 v75, v0
	v_mov_b32_e32 v92, v0
	v_mov_b32_e32 v93, v0
	v_mov_b32_e32 v94, v0
	v_mov_b32_e32 v95, v0
	v_mov_b32_e32 v88, v0
	v_mov_b32_e32 v89, v0
	v_mov_b32_e32 v90, v0
	v_mov_b32_e32 v91, v0
	v_mov_b32_e32 v108, v0
	v_mov_b32_e32 v109, v0
	v_mov_b32_e32 v110, v0
	v_mov_b32_e32 v111, v0
	v_mov_b32_e32 v104, v0
	v_mov_b32_e32 v105, v0
	v_mov_b32_e32 v106, v0
	v_mov_b32_e32 v107, v0
	v_mov_b32_e32 v120, v0
	v_mov_b32_e32 v121, v0
	v_mov_b32_e32 v122, v0
	v_mov_b32_e32 v123, v0
	v_mov_b32_e32 v124, v0
	v_mov_b32_e32 v125, v0
	v_mov_b32_e32 v126, v0
	v_mov_b32_e32 v127, v0
	s_cmp_eq_u32 s101, 1
	s_cbranch_scc0 .Lsp_5
	s_setprio 3

; template <class Epi>
; __device__ __forceinline__ void gemm_phase(PG8_LAS unsigned char* lds, const Gemm g, const StaticOrder& S, const Epi& E) {
;     ...
;         const bool has_next = S.next(ui + 1, nxt);
;         const char* nA = has_next ? (const char*)g.A + (size_t)nxt.pm * tstepA : cA; const char* nB = has_next ? (const char*)g.Bt + (size_t)nxt.pn * tstepB : cB;
;     ...
; #pragma unroll
;         for (int a = 0; a < 2; ++a)
; #pragma unroll
;             for (int b = 0; b < 2; ++b)
; #pragma unroll
;                 for (int m = 0; m < 4; ++m)
; #pragma unroll
;                     for (int n = 0; n < 2; ++n) acc[a][b][m][n] = (f32x4){0.f, 0.f, 0.f, 0.f};
;         cur = nxt; cA = nA; cB = nB; ++ui;
.LBB0_1085:
	s_ashr_i32 s39, s38, 31
	v_cmp_lt_i64_e32 vcc, s[0:1], v[150:151]
	s_lshl_b64 s[0:1], s[38:39], 20
	s_add_u32 s40, s76, s0
	s_addc_u32 s41, s77, s1
	s_and_b64 s[0:1], vcc, exec
	s_cselect_b32 s39, s41, s7
	s_cselect_b32 s59, s40, s6
	s_ashr_i32 s37, s36, 31
	s_lshl_b64 s[0:1], s[36:37], 20
	v_readlane_b32 s42, v253, 28
	v_readlane_b32 s43, v253, 29
	s_add_u32 s42, s42, s0
	s_addc_u32 s43, s43, s1
	s_and_b64 s[0:1], vcc, exec
	s_cselect_b32 s37, s43, s5
	s_cselect_b32 s60, s42, s4
	s_add_u32 s0, s6, 0x80080
	s_addc_u32 s1, s7, 0
	s_add_u32 s61, s4, 0x100
	v_mov_b32_e32 v8, 0
	s_addc_u32 s62, s5, 0
	s_mov_b32 s63, -2
	v_mov_b32_e32 v9, v8
	v_mov_b32_e32 v10, v8
	v_mov_b32_e32 v11, v8
	v_mov_b32_e32 v16, v8
	v_mov_b32_e32 v17, v8
	v_mov_b32_e32 v18, v8
	v_mov_b32_e32 v19, v8
	v_mov_b32_e32 v24, v8
	v_mov_b32_e32 v25, v8
	v_mov_b32_e32 v26, v8
	v_mov_b32_e32 v27, v8
	v_mov_b32_e32 v32, v8
	v_mov_b32_e32 v33, v8
	v_mov_b32_e32 v34, v8
	v_mov_b32_e32 v35, v8
	v_mov_b32_e32 v40, v8
	v_mov_b32_e32 v41, v8
	v_mov_b32_e32 v42, v8
	v_mov_b32_e32 v43, v8
	v_mov_b32_e32 v48, v8
	v_mov_b32_e32 v49, v8
	v_mov_b32_e32 v50, v8
	v_mov_b32_e32 v51, v8
	v_mov_b32_e32 v56, v8
	v_mov_b32_e32 v57, v8
	v_mov_b32_e32 v58, v8
	v_mov_b32_e32 v59, v8
	v_mov_b32_e32 v64, v8
	v_mov_b32_e32 v65, v8
	v_mov_b32_e32 v66, v8
	v_mov_b32_e32 v67, v8
	v_mov_b32_e32 v12, v8
	v_mov_b32_e32 v13, v8
	v_mov_b32_e32 v14, v8
	v_mov_b32_e32 v15, v8
	v_mov_b32_e32 v20, v8
	v_mov_b32_e32 v21, v8
	v_mov_b32_e32 v22, v8
	v_mov_b32_e32 v23, v8
	v_mov_b32_e32 v28, v8
	v_mov_b32_e32 v29, v8
	v_mov_b32_e32 v30, v8
	v_mov_b32_e32 v31, v8
	v_mov_b32_e32 v36, v8
	v_mov_b32_e32 v37, v8
	v_mov_b32_e32 v38, v8
	v_mov_b32_e32 v39, v8
	v_mov_b32_e32 v44, v8
	v_mov_b32_e32 v45, v8
	v_mov_b32_e32 v46, v8
	v_mov_b32_e32 v47, v8
	v_mov_b32_e32 v52, v8
	v_mov_b32_e32 v53, v8
	v_mov_b32_e32 v54, v8
	v_mov_b32_e32 v55, v8
	v_mov_b32_e32 v60, v8
	v_mov_b32_e32 v61, v8
	v_mov_b32_e32 v62, v8
	v_mov_b32_e32 v63, v8
	v_mov_b32_e32 v68, v8
	v_mov_b32_e32 v69, v8
	v_mov_b32_e32 v70, v8
	v_mov_b32_e32 v71, v8
	v_mov_b32_e32 v72, v8
	v_mov_b32_e32 v73, v8
	v_mov_b32_e32 v74, v8
	v_mov_b32_e32 v75, v8
	v_mov_b32_e32 v80, v8
	v_mov_b32_e32 v81, v8
	v_mov_b32_e32 v82, v8
	v_mov_b32_e32 v83, v8
	v_mov_b32_e32 v88, v8
	v_mov_b32_e32 v89, v8
	v_mov_b32_e32 v90, v8
	v_mov_b32_e32 v91, v8
	v_mov_b32_e32 v96, v8
	v_mov_b32_e32 v97, v8
	v_mov_b32_e32 v98, v8
	v_mov_b32_e32 v99, v8
	v_mov_b32_e32 v104, v8
	v_mov_b32_e32 v105, v8
	v_mov_b32_e32 v106, v8
	v_mov_b32_e32 v107, v8
	v_mov_b32_e32 v112, v8
	v_mov_b32_e32 v113, v8
	v_mov_b32_e32 v114, v8
	v_mov_b32_e32 v115, v8
	v_mov_b32_e32 v120, v8
	v_mov_b32_e32 v121, v8
	v_mov_b32_e32 v122, v8
	v_mov_b32_e32 v123, v8
	v_mov_b32_e32 v128, v8
	v_mov_b32_e32 v129, v8
	v_mov_b32_e32 v130, v8
	v_mov_b32_e32 v131, v8
	v_mov_b32_e32 v76, v8
	v_mov_b32_e32 v77, v8
	v_mov_b32_e32 v78, v8
	v_mov_b32_e32 v79, v8
	v_mov_b32_e32 v84, v8
	v_mov_b32_e32 v85, v8
	v_mov_b32_e32 v86, v8
	v_mov_b32_e32 v87, v8
	v_mov_b32_e32 v92, v8
	v_mov_b32_e32 v93, v8
	v_mov_b32_e32 v94, v8
	v_mov_b32_e32 v95, v8
	v_mov_b32_e32 v100, v8
	v_mov_b32_e32 v101, v8
	v_mov_b32_e32 v102, v8
	v_mov_b32_e32 v103, v8
	v_mov_b32_e32 v108, v8
	v_mov_b32_e32 v109, v8
	v_mov_b32_e32 v110, v8
	v_mov_b32_e32 v111, v8
	v_mov_b32_e32 v116, v8
	v_mov_b32_e32 v117, v8
	v_mov_b32_e32 v118, v8
	v_mov_b32_e32 v119, v8
	v_mov_b32_e32 v124, v8
	v_mov_b32_e32 v125, v8
	v_mov_b32_e32 v126, v8
	v_mov_b32_e32 v127, v8
	v_mov_b32_e32 v132, v8
	v_mov_b32_e32 v133, v8
	v_mov_b32_e32 v134, v8
	v_mov_b32_e32 v135, v8
	s_cmp_eq_u32 s101, 1
	s_cbranch_scc0 .Lsp_6
	s_setprio 3

; template <class Epi>
; __device__ __forceinline__ void gemm_phase(PG8_LAS unsigned char* lds, const Gemm g, const StaticOrder& S, const Epi& E) {
;     ...
;         const bool has_next = S.next(ui + 1, nxt);
;         const char* nA = has_next ? (const char*)g.A + (size_t)nxt.pm * tstepA : cA; const char* nB = has_next ? (const char*)g.Bt + (size_t)nxt.pn * tstepB : cB;
;     ...
; #pragma unroll
;         for (int a = 0; a < 2; ++a)
; #pragma unroll
;             for (int b = 0; b < 2; ++b)
; #pragma unroll
;                 for (int m = 0; m < 4; ++m)
; #pragma unroll
;                     for (int n = 0; n < 2; ++n) acc[a][b][m][n] = (f32x4){0.f, 0.f, 0.f, 0.f};
;         cur = nxt; cA = nA; cB = nB; ++ui;
.LBB0_1169:
	s_add_u32 s10, s10, 0x160080
	s_addc_u32 s11, s11, 0
	s_add_u32 s36, s12, 0x100
	v_mov_b32_e32 v4, 0
	s_addc_u32 s37, s13, 0
	s_mov_b32 s38, -2
	v_mov_b32_e32 v5, v4
	v_mov_b32_e32 v6, v4
	v_mov_b32_e32 v7, v4
	v_mov_b32_e32 v0, v4
	v_mov_b32_e32 v1, v4
	v_mov_b32_e32 v2, v4
	v_mov_b32_e32 v3, v4
	v_mov_b32_e32 v20, v4
	v_mov_b32_e32 v21, v4
	v_mov_b32_e32 v22, v4
	v_mov_b32_e32 v23, v4
	v_mov_b32_e32 v16, v4
	v_mov_b32_e32 v17, v4
	v_mov_b32_e32 v18, v4
	v_mov_b32_e32 v19, v4
	v_mov_b32_e32 v36, v4
	v_mov_b32_e32 v37, v4
	v_mov_b32_e32 v38, v4
	v_mov_b32_e32 v39, v4
	v_mov_b32_e32 v32, v4
	v_mov_b32_e32 v33, v4
	v_mov_b32_e32 v34, v4
	v_mov_b32_e32 v35, v4
	v_mov_b32_e32 v52, v4
	v_mov_b32_e32 v53, v4
	v_mov_b32_e32 v54, v4
	v_mov_b32_e32 v55, v4
	v_mov_b32_e32 v48, v4
	v_mov_b32_e32 v49, v4
	v_mov_b32_e32 v50, v4
	v_mov_b32_e32 v51, v4
	v_mov_b32_e32 v12, v4
	v_mov_b32_e32 v13, v4
	v_mov_b32_e32 v14, v4
	v_mov_b32_e32 v15, v4
	v_mov_b32_e32 v8, v4
	v_mov_b32_e32 v9, v4
	v_mov_b32_e32 v10, v4
	v_mov_b32_e32 v11, v4
	v_mov_b32_e32 v28, v4
	v_mov_b32_e32 v29, v4
	v_mov_b32_e32 v30, v4
	v_mov_b32_e32 v31, v4
	v_mov_b32_e32 v24, v4
	v_mov_b32_e32 v25, v4
	v_mov_b32_e32 v26, v4
	v_mov_b32_e32 v27, v4
	v_mov_b32_e32 v44, v4
	v_mov_b32_e32 v45, v4
	v_mov_b32_e32 v46, v4
	v_mov_b32_e32 v47, v4
	v_mov_b32_e32 v40, v4
	v_mov_b32_e32 v41, v4
	v_mov_b32_e32 v42, v4
	v_mov_b32_e32 v43, v4
	v_mov_b32_e32 v60, v4
	v_mov_b32_e32 v61, v4
	v_mov_b32_e32 v62, v4
	v_mov_b32_e32 v63, v4
	v_mov_b32_e32 v56, v4
	v_mov_b32_e32 v57, v4
	v_mov_b32_e32 v58, v4
	v_mov_b32_e32 v59, v4
	v_mov_b32_e32 v68, v4
	v_mov_b32_e32 v69, v4
	v_mov_b32_e32 v70, v4
	v_mov_b32_e32 v71, v4
	v_mov_b32_e32 v64, v4
	v_mov_b32_e32 v65, v4
	v_mov_b32_e32 v66, v4
	v_mov_b32_e32 v67, v4
	v_mov_b32_e32 v84, v4
	v_mov_b32_e32 v85, v4
	v_mov_b32_e32 v86, v4
	v_mov_b32_e32 v87, v4
	v_mov_b32_e32 v80, v4
	v_mov_b32_e32 v81, v4
	v_mov_b32_e32 v82, v4
	v_mov_b32_e32 v83, v4
	v_mov_b32_e32 v96, v4
	v_mov_b32_e32 v97, v4
	v_mov_b32_e32 v98, v4
	v_mov_b32_e32 v99, v4
	v_mov_b32_e32 v100, v4
	v_mov_b32_e32 v101, v4
	v_mov_b32_e32 v102, v4
	v_mov_b32_e32 v103, v4
	v_mov_b32_e32 v112, v4
	v_mov_b32_e32 v113, v4
	v_mov_b32_e32 v114, v4
	v_mov_b32_e32 v115, v4
	v_mov_b32_e32 v116, v4
	v_mov_b32_e32 v117, v4
	v_mov_b32_e32 v118, v4
	v_mov_b32_e32 v119, v4
	v_mov_b32_e32 v76, v4
	v_mov_b32_e32 v77, v4
	v_mov_b32_e32 v78, v4
	v_mov_b32_e32 v79, v4
	v_mov_b32_e32 v72, v4
	v_mov_b32_e32 v73, v4
	v_mov_b32_e32 v74, v4
	v_mov_b32_e32 v75, v4
	v_mov_b32_e32 v92, v4
	v_mov_b32_e32 v93, v4
	v_mov_b32_e32 v94, v4
	v_mov_b32_e32 v95, v4
	v_mov_b32_e32 v88, v4
	v_mov_b32_e32 v89, v4
	v_mov_b32_e32 v90, v4
	v_mov_b32_e32 v91, v4
	v_mov_b32_e32 v104, v4
	v_mov_b32_e32 v105, v4
	v_mov_b32_e32 v106, v4
	v_mov_b32_e32 v107, v4
	v_mov_b32_e32 v108, v4
	v_mov_b32_e32 v109, v4
	v_mov_b32_e32 v110, v4
	v_mov_b32_e32 v111, v4
	v_mov_b32_e32 v120, v4
	v_mov_b32_e32 v121, v4
	v_mov_b32_e32 v122, v4
	v_mov_b32_e32 v123, v4
	v_mov_b32_e32 v124, v4
	v_mov_b32_e32 v125, v4
	v_mov_b32_e32 v126, v4
	v_mov_b32_e32 v127, v4
	s_cmp_eq_u32 s101, 1
	s_cbranch_scc0 .Lsp_7
	s_setprio 3
